# prologue rmsnorm loop: loop-invariant gain vectors loaded once before the loop; plus all earlier changes (merge/down epilogue load batching, attention Y-phase rewrite)
# baseline (speedup 1.0000x reference)
; DI void p0_prologue(const Args& a, LAS unsigned char* lds, int tid, int lane, int wave) {
;     ...
;     const int gw = bid * 8 + wave, nw = G * 8;
;     { const float* g = a.in[6]; bf16* XN = (bf16*)(ws + WS_XN);
;       for (int row = gw; row < MT; row += nw) {
;           const float* xr = row < MP ? a.in[0] + (size_t)row * 2048 : a.in[1] + (size_t)(row - MP) * 2048;
;           f32x4 v[8]; float ss = 0.f;
; #pragma unroll
;           for (int i = 0; i < 8; ++i) { v[i] = ((const f32x4*)xr)[lane + 64 * i]; ss += v[i][0] * v[i][0] + v[i][1] * v[i][1] + v[i][2] * v[i][2] + v[i][3] * v[i][3]; }
;           ss = wave_sum(ss); const float rstd = rsqrtf(ss * (1.0f / 2048.0f) + EPS);
; #pragma unroll
;           for (int i = 0; i < 8; ++i) { const f32x4 gv = ((const f32x4*)g)[lane + 64 * i];
.LBB0_45:
	s_or_b64 exec, exec, s[0:1]
	s_lshl_b32 s0, s10, 3
	v_readlane_b32 s1, v254, 18
	s_add_i32 s0, s1, s0
	s_cmpk_gt_i32 s0, 0x41ff
	s_cbranch_scc1 .LBB0_50
	v_mbcnt_lo_u32_b32 v1, -1, 0
	v_mbcnt_hi_u32_b32 v3, -1, v1
	v_and_b32_e32 v1, 64, v3
	v_add_u32_e32 v5, 64, v1
	v_xor_b32_e32 v1, 32, v3
	v_cmp_lt_i32_e32 vcc, v1, v5
	v_xor_b32_e32 v7, 16, v3
	v_lshlrev_b32_e32 v18, 4, v160
	v_cndmask_b32_e32 v1, v3, v1, vcc
	v_cmp_lt_i32_e32 vcc, v7, v5
	v_mov_b32_e32 v19, 0
	v_lshl_add_u64 v[20:21], s[48:49], 0, v[18:19]
	v_cndmask_b32_e32 v7, v3, v7, vcc
	v_mov_b32_e32 v23, v19
	v_mov_b32_e32 v25, v19
	v_mov_b32_e32 v27, v19
	v_mov_b32_e32 v29, v19
	v_lshlrev_b32_e32 v19, 2, v7
	v_xor_b32_e32 v7, 8, v3
	v_cmp_lt_i32_e32 vcc, v7, v5
	s_lshl_b32 s4, s34, 3
	s_add_u32 s8, s28, 0x3800000
	v_cndmask_b32_e32 v7, v3, v7, vcc
	v_lshlrev_b32_e32 v30, 2, v7
	v_xor_b32_e32 v7, 4, v3
	v_cmp_lt_i32_e32 vcc, v7, v5
	s_addc_u32 s9, s29, 0
	s_ashr_i32 s1, s0, 31
	v_cndmask_b32_e32 v7, v3, v7, vcc
	v_lshlrev_b32_e32 v31, 2, v7
	v_xor_b32_e32 v7, 2, v3
	v_cmp_lt_i32_e32 vcc, v7, v5
	v_or_b32_e32 v2, 0x100, v160
	v_or_b32_e32 v4, 0x140, v160
	v_cndmask_b32_e32 v7, v3, v7, vcc
	v_lshlrev_b32_e32 v32, 2, v7
	v_xor_b32_e32 v7, 1, v3
	v_or_b32_e32 v6, 0x180, v160
	v_or_b32_e32 v8, 0x1c0, v160
	v_lshlrev_b32_e32 v10, 2, v160
	v_cmp_lt_i32_e32 vcc, v7, v5
	s_ashr_i32 s5, s4, 31
	s_waitcnt lgkmcnt(0)
	s_lshl_b64 s[12:13], s[0:1], 13
	v_or_b32_e32 v12, 0x100, v10
	v_or_b32_e32 v14, 0x200, v10
	v_or_b32_e32 v16, 0x300, v10
	v_lshlrev_b32_e32 v22, 4, v2
	v_lshlrev_b32_e32 v44, 2, v2
	v_lshlrev_b32_e32 v24, 4, v4
	v_lshlrev_b32_e32 v46, 2, v4
	v_lshlrev_b32_e32 v26, 4, v6
	v_lshlrev_b32_e32 v48, 2, v6
	v_lshlrev_b32_e32 v28, 4, v8
	v_lshlrev_b32_e32 v50, 2, v8
	v_cndmask_b32_e32 v3, v3, v7, vcc
	s_add_u32 s12, s36, s12
	v_lshl_add_u64 v[22:23], s[48:49], 0, v[22:23]
	v_lshl_add_u64 v[24:25], s[48:49], 0, v[24:25]
	v_lshl_add_u64 v[26:27], s[48:49], 0, v[26:27]
	v_lshl_add_u64 v[28:29], s[48:49], 0, v[28:29]
	s_mov_b32 s7, 0
	v_lshlrev_b32_e32 v1, 2, v1
	v_lshlrev_b32_e32 v33, 2, v3
	s_addc_u32 s13, s37, s13
	s_lshl_b64 s[14:15], s[4:5], 13
	v_lshlrev_b32_e32 v34, 4, v2
	v_lshlrev_b32_e32 v35, 4, v4
	v_lshlrev_b32_e32 v36, 4, v6
	v_lshlrev_b32_e32 v37, 4, v8
	v_mov_b32_e32 v38, 0x358637bd
	s_mov_b32 s11, 0x800000
	v_lshlrev_b32_e32 v39, 1, v10
	v_lshlrev_b32_e32 v40, 1, v12
	v_lshlrev_b32_e32 v41, 1, v14
	v_lshlrev_b32_e32 v42, 1, v16
	v_lshlrev_b32_e32 v43, 1, v44
	v_lshlrev_b32_e32 v44, 1, v46
	v_lshlrev_b32_e32 v45, 1, v48
	v_lshlrev_b32_e32 v46, 1, v50
	global_load_dwordx4 v[100:103], v[20:21], off
	global_load_dwordx4 v[104:107], v[20:21], off offset:1024
	global_load_dwordx4 v[108:111], v[20:21], off offset:2048
	global_load_dwordx4 v[112:115], v[20:21], off offset:3072
	global_load_dwordx4 v[116:119], v[22:23], off
	global_load_dwordx4 v[120:123], v[24:25], off
	global_load_dwordx4 v[124:127], v[26:27], off
	global_load_dwordx4 v[128:131], v[28:29], off
	s_branch .LBB0_48
; DI unsigned pk2(float lo, float hi) { f32x2_t v = {lo, hi}; bf16x2_t b = __builtin_convertvector(v, bf16x2_t); return __builtin_bit_cast(unsigned, b); }
; DI void p0_prologue(const Args& a, LAS unsigned char* lds, int tid, int lane, int wave) {
;     ...
;       for (int row = gw; row < MT; row += nw) {
;           const float* xr = row < MP ? a.in[0] + (size_t)row * 2048 : a.in[1] + (size_t)(row - MP) * 2048;
;           f32x4 v[8]; float ss = 0.f;
; #pragma unroll
;           for (int i = 0; i < 8; ++i) { v[i] = ((const f32x4*)xr)[lane + 64 * i]; ss += v[i][0] * v[i][0] + v[i][1] * v[i][1] + v[i][2] * v[i][2] + v[i][3] * v[i][3]; }
;           ss = wave_sum(ss); const float rstd = rsqrtf(ss * (1.0f / 2048.0f) + EPS);
; #pragma unroll
;           for (int i = 0; i < 8; ++i) { const f32x4 gv = ((const f32x4*)g)[lane + 64 * i];
;               u32x2 w; w.x = pk2(v[i][0] * rstd * gv[0], v[i][1] * rstd * gv[1]); w.y = pk2(v[i][2] * rstd * gv[2], v[i][3] * rstd * gv[3]);
;               *(u32x2*)(XN + (size_t)row * 2048 + 4 * (lane + 64 * i)) = w; }
.LBB0_47:
	global_load_dwordx4 v[14:17], v34, s[18:19]
	global_load_dwordx4 v[6:9], v35, s[18:19]
	global_load_dwordx4 v[10:13], v36, s[18:19]
	global_load_dwordx4 v[2:5], v37, s[18:19]
	global_load_dwordx4 v[48:51], v18, s[18:19]
	global_load_dwordx4 v[52:55], v18, s[18:19] offset:1024
	global_load_dwordx4 v[56:59], v18, s[18:19] offset:2048
	global_load_dwordx4 v[60:63], v18, s[18:19] offset:3072
	s_lshl_b64 s[16:17], s[16:17], 12
	s_add_u32 s16, s8, s16
	s_addc_u32 s17, s9, s17
	s_add_u32 s0, s0, s4
	s_addc_u32 s1, s1, s5
	s_add_u32 s12, s12, s14
	s_addc_u32 s13, s13, s15
	s_cmpk_lt_i32 s0, 0x4200
	s_waitcnt vmcnt(7)
	v_mov_b32_e32 v70, v15
	s_waitcnt vmcnt(6)
	v_mov_b32_e32 v71, v7
	v_mov_b32_e32 v68, v14
	v_mov_b32_e32 v69, v6
	s_waitcnt vmcnt(3)
	v_mul_f32_e32 v47, v49, v49
	s_waitcnt vmcnt(2)
	v_mul_f32_e32 v84, v53, v53
	s_waitcnt vmcnt(1)
	v_mul_f32_e32 v85, v57, v57
	v_fmac_f32_e32 v47, v48, v48
	v_fmac_f32_e32 v84, v52, v52
	s_waitcnt vmcnt(0)
	v_mul_f32_e32 v86, v61, v61
	v_fmac_f32_e32 v85, v56, v56
	v_fmac_f32_e32 v47, v50, v50
	v_fmac_f32_e32 v84, v54, v54
	v_pk_mul_f32 v[70:71], v[70:71], v[70:71]
	v_fmac_f32_e32 v86, v60, v60
	v_fmac_f32_e32 v85, v58, v58
	v_fmac_f32_e32 v47, v51, v51
	v_fmac_f32_e32 v84, v55, v55
	v_mov_b32_e32 v72, v16
	v_mov_b32_e32 v73, v8
	v_mov_b32_e32 v76, v11
	v_mov_b32_e32 v77, v3
	v_pk_fma_f32 v[68:69], v[68:69], v[68:69], v[70:71]
	v_fmac_f32_e32 v86, v62, v62
	v_fmac_f32_e32 v85, v59, v59
	v_add_f32_e32 v47, v47, v84
	v_mov_b32_e32 v74, v10
	v_mov_b32_e32 v75, v2
	v_mov_b32_e32 v78, v17
	v_mov_b32_e32 v79, v9
	v_pk_mul_f32 v[76:77], v[76:77], v[76:77]
	v_pk_fma_f32 v[68:69], v[72:73], v[72:73], v[68:69]
	v_fmac_f32_e32 v86, v63, v63
	v_add_f32_e32 v47, v47, v85
	v_mov_b32_e32 v80, v12
	v_mov_b32_e32 v81, v4
	v_pk_fma_f32 v[70:71], v[74:75], v[74:75], v[76:77]
	v_pk_fma_f32 v[68:69], v[78:79], v[78:79], v[68:69]
	v_add_f32_e32 v47, v47, v86
	v_mov_b32_e32 v82, v13
	v_mov_b32_e32 v83, v5
	v_pk_fma_f32 v[70:71], v[80:81], v[80:81], v[70:71]
	v_add_f32_e32 v47, v47, v68
	v_pk_fma_f32 v[70:71], v[82:83], v[82:83], v[70:71]
	v_add_f32_e32 v47, v47, v69
	v_add_f32_e32 v47, v47, v70
	v_add_f32_e32 v47, v47, v71
	ds_bpermute_b32 v68, v1, v47
	s_waitcnt lgkmcnt(0)
	v_add_f32_e32 v47, v47, v68
	ds_bpermute_b32 v68, v19, v47
	s_waitcnt lgkmcnt(0)
	v_add_f32_e32 v47, v47, v68
	ds_bpermute_b32 v68, v30, v47
	s_waitcnt lgkmcnt(0)
	v_add_f32_e32 v47, v47, v68
	ds_bpermute_b32 v68, v31, v47
	s_waitcnt lgkmcnt(0)
	v_add_f32_e32 v47, v47, v68
	ds_bpermute_b32 v68, v32, v47
	s_waitcnt lgkmcnt(0)
	v_add_f32_e32 v47, v47, v68
	ds_bpermute_b32 v68, v33, v47
	s_waitcnt lgkmcnt(0)
	v_add_f32_e32 v47, v47, v68
	v_fmamk_f32 v47, v47, 0x3a000000, v38
	v_mul_f32_e32 v68, 0x4b800000, v47
	v_cmp_gt_f32_e32 vcc, s11, v47
	s_nop 1
	v_cndmask_b32_e32 v47, v47, v68, vcc
	v_rsq_f32_e32 v47, v47
	s_nop 0
	v_mul_f32_e32 v68, 0x45800000, v47
	v_cndmask_b32_e32 v68, v47, v68, vcc
	v_pk_mul_f32 v[48:49], v[48:49], v[68:69] op_sel_hi:[1,0]
	v_pk_mul_f32 v[50:51], v[50:51], v[68:69] op_sel_hi:[1,0]
	v_pk_mul_f32 v[48:49], v[100:101], v[48:49]
	v_pk_mul_f32 v[50:51], v[102:103], v[50:51]
	v_cvt_pk_bf16_f32 v48, v48, v49
	v_cvt_pk_bf16_f32 v49, v50, v51
	global_store_dwordx2 v39, v[48:49], s[16:17]
	v_pk_mul_f32 v[52:53], v[52:53], v[68:69] op_sel_hi:[1,0]
	v_pk_mul_f32 v[54:55], v[54:55], v[68:69] op_sel_hi:[1,0]
	v_pk_mul_f32 v[14:15], v[14:15], v[68:69] op_sel_hi:[1,0]
	v_pk_mul_f32 v[16:17], v[16:17], v[68:69] op_sel_hi:[1,0]
	v_pk_mul_f32 v[6:7], v[6:7], v[68:69] op_sel_hi:[1,0]
	v_pk_mul_f32 v[8:9], v[8:9], v[68:69] op_sel_hi:[1,0]
	v_pk_mul_f32 v[10:11], v[10:11], v[68:69] op_sel_hi:[1,0]
	v_pk_mul_f32 v[12:13], v[12:13], v[68:69] op_sel_hi:[1,0]
	v_pk_mul_f32 v[2:3], v[2:3], v[68:69] op_sel_hi:[1,0]
	v_pk_mul_f32 v[4:5], v[4:5], v[68:69] op_sel_hi:[1,0]
	v_pk_mul_f32 v[48:49], v[104:105], v[52:53]
	v_pk_mul_f32 v[50:51], v[106:107], v[54:55]
	v_cvt_pk_bf16_f32 v48, v48, v49
	v_cvt_pk_bf16_f32 v49, v50, v51
	global_store_dwordx2 v40, v[48:49], s[16:17]
	v_pk_mul_f32 v[52:53], v[56:57], v[68:69] op_sel_hi:[1,0]
	v_pk_mul_f32 v[54:55], v[58:59], v[68:69] op_sel_hi:[1,0]
	v_pk_mul_f32 v[48:49], v[108:109], v[52:53]
	v_pk_mul_f32 v[50:51], v[110:111], v[54:55]
	v_cvt_pk_bf16_f32 v48, v48, v49
	v_cvt_pk_bf16_f32 v49, v50, v51
	global_store_dwordx2 v41, v[48:49], s[16:17]
	v_pk_mul_f32 v[52:53], v[60:61], v[68:69] op_sel_hi:[1,0]
	v_pk_mul_f32 v[54:55], v[62:63], v[68:69] op_sel_hi:[1,0]
	v_pk_mul_f32 v[48:49], v[112:113], v[52:53]
	v_pk_mul_f32 v[50:51], v[114:115], v[54:55]
	v_cvt_pk_bf16_f32 v48, v48, v49
	v_cvt_pk_bf16_f32 v49, v50, v51
	global_store_dwordx2 v42, v[48:49], s[16:17]
	v_pk_mul_f32 v[14:15], v[116:117], v[14:15]
	v_pk_mul_f32 v[16:17], v[118:119], v[16:17]
	v_cvt_pk_bf16_f32 v14, v14, v15
	v_cvt_pk_bf16_f32 v15, v16, v17
	global_store_dwordx2 v43, v[14:15], s[16:17]
	v_pk_mul_f32 v[6:7], v[120:121], v[6:7]
	v_pk_mul_f32 v[8:9], v[122:123], v[8:9]
	v_cvt_pk_bf16_f32 v6, v6, v7
	v_cvt_pk_bf16_f32 v7, v8, v9
	global_store_dwordx2 v44, v[6:7], s[16:17]
	v_pk_mul_f32 v[6:7], v[10:11], v[124:125]
	v_pk_mul_f32 v[8:9], v[12:13], v[126:127]
	v_cvt_pk_bf16_f32 v6, v6, v7
	v_cvt_pk_bf16_f32 v7, v8, v9
	global_store_dwordx2 v45, v[6:7], s[16:17]
	v_pk_mul_f32 v[2:3], v[2:3], v[128:129]
	v_pk_mul_f32 v[4:5], v[4:5], v[130:131]
	v_cvt_pk_bf16_f32 v2, v2, v3
	v_cvt_pk_bf16_f32 v3, v4, v5
	global_store_dwordx2 v46, v[2:3], s[16:17]
	s_cbranch_scc0 .LBB0_50
